# MoBA prep: k-mean DPP reduction chains batched 8 at a time (no hazard nops, one exec toggle per batch)
# speedup vs baseline: 1.0028x; 1.0028x over previous
; template <int CTRL> __device__ __forceinline__ float dpp_f(float x) { return __int_as_float(__builtin_amdgcn_update_dpp(0, __float_as_int(x), CTRL, 0xF, 0xF, true)); }
; __device__ __forceinline__ void moba_prep_phase(unsigned char* lds, const bf16_t* H, const float* cosT, const float* sinT, const float* qgain, const float* kgain,
;                                                 bf16_t* Qn, bf16_t* Kimg, bf16_t* VT, float* kmean, int bid, int G, int tid) {
;     ...
;         const int bn = pit / 12, h = pit - bn * 12, b = bn >> 6, n = bn & 63, bh = b * 12 + h;
;         const int tk = tid >> 1, half = tid & 1, t = n * 256 + tk;
;         const bf16_t* hrow = H + (size_t)(b * SEQ + t) * NMOBA + h * 64 + half * 32;
;         if (bn != cur_bn) {
;             cur_bn = bn;
; #pragma unroll
;             for (int i = 0; i < 8; ++i) { const f32x4 a = *(const f32x4*)(cosT + (size_t)t * 32 + 4 * i), bq = *(const f32x4*)(sinT + (size_t)t * 32 + 4 * i);
;                 cs[4 * i] = a.x; cs[4 * i + 1] = a.y; cs[4 * i + 2] = a.z; cs[4 * i + 3] = a.w; sn[4 * i] = bq.x; sn[4 * i + 1] = bq.y; sn[4 * i + 2] = bq.z; sn[4 * i + 3] = bq.w; }
;         }
;         u32x4 raw[3][4];
; #pragma unroll
;         for (int which = 0; which < 3; ++which)
; #pragma unroll
;             for (int i = 0; i < 4; ++i) raw[which][i] = *(const u32x4*)(hrow + which * 768 + 8 * i);
;         float x[32];
; #pragma unroll
;         for (int which = 0; which < 2; ++which) {
;             const float* gn = which ? kgain : qgain;
; #pragma unroll
;             for (int i = 0; i < 4; ++i) unpack8(raw[which][i], x + 8 * i);
;             float sq = 0.f;
; #pragma unroll
;             for (int i = 0; i < 32; ++i) sq += x[i] * x[i];
;             sq += dpp_f<DPP_XOR1>(sq);
;             const float rs = rsqrtf(sq * (1.0f / 64.0f) + 1e-6f);
; #pragma unroll
;             for (int i = 0; i < 32; ++i) { const float xn = x[i] * rs * gn[half * 32 + i]; const float other = dpp_f<DPP_XOR1>(xn); x[i] = half ? (xn * cs[i] + other * sn[i]) : (xn * cs[i] - other * sn[i]); }
.LBB0_505:
	s_ashr_i32 s25, s1, 6
	s_waitcnt vmcnt(16)
	v_lshl_add_u32 v66, s25, 14, v64
	v_mov_b64_e32 v[64:65], s[78:79]
	s_mul_i32 s27, s1, 12
	v_mad_i64_i32 v[64:65], s[40:41], v66, s60, v[64:65]
	s_mulk_i32 s1, 0xfd00
	s_add_i32 s40, s23, s1
	s_ashr_i32 s41, s40, 31
	v_lshl_add_u64 v[64:65], s[40:41], 1, v[64:65]
	v_lshl_add_u64 v[64:65], v[64:65], 0, v[138:139]
	global_load_dwordx4 v[168:171], v[64:65], off offset:48
	global_load_dwordx4 v[132:135], v[64:65], off offset:32
	global_load_dwordx4 v[148:151], v[64:65], off offset:16
	global_load_dwordx4 v[98:101], v[64:65], off
	global_load_dwordx4 v[80:83], v[64:65], off offset:1584
	global_load_dwordx4 v[84:87], v[64:65], off offset:1568
	global_load_dwordx4 v[88:91], v[64:65], off offset:1552
	global_load_dwordx4 v[92:95], v[64:65], off offset:1536
	global_load_dwordx4 v[76:79], v[64:65], off offset:3072
	global_load_dwordx4 v[72:75], v[64:65], off offset:3088
	global_load_dwordx4 v[68:71], v[64:65], off offset:3104
	s_nop 0
	global_load_dwordx4 v[64:67], v[64:65], off offset:3120
	s_mul_i32 s26, s25, 12
	s_sub_i32 s26, s26, s27
	s_add_i32 s26, s22, s26
	s_lshl_b32 s1, s26, 6
	s_or_b32 s46, s1, s0
	s_ashr_i32 s47, s46, 31
	s_ashr_i32 s27, s26, 31
	s_lshl_b64 s[40:41], s[46:47], 15
	s_lshl_b64 s[0:1], s[26:27], 21
	s_add_u32 s0, s62, s0
	s_addc_u32 s1, s63, s1
	v_lshl_add_u64 v[130:131], s[0:1], 0, v[96:97]
	s_waitcnt vmcnt(10)
	v_lshlrev_b32_e32 v164, 16, v134
	v_and_b32_e32 v163, 0xffff0000, v134
	s_waitcnt vmcnt(8)
	v_and_b32_e32 v111, 0xffff0000, v98
	v_lshlrev_b32_e32 v172, 16, v98
	v_mul_f32_e32 v134, v111, v111
	v_lshlrev_b32_e32 v110, 16, v99
	v_fmac_f32_e32 v134, v172, v172
	v_and_b32_e32 v109, 0xffff0000, v99
	v_fmac_f32_e32 v134, v110, v110
	v_lshlrev_b32_e32 v108, 16, v100
	v_fmac_f32_e32 v134, v109, v109
	v_and_b32_e32 v107, 0xffff0000, v100
	v_fmac_f32_e32 v134, v108, v108
	v_lshlrev_b32_e32 v106, 16, v101
	v_fmac_f32_e32 v134, v107, v107
	v_and_b32_e32 v105, 0xffff0000, v101
	v_fmac_f32_e32 v134, v106, v106
	v_lshlrev_b32_e32 v104, 16, v148
	v_fmac_f32_e32 v134, v105, v105
	v_and_b32_e32 v103, 0xffff0000, v148
	v_fmac_f32_e32 v134, v104, v104
	v_lshlrev_b32_e32 v102, 16, v149
	v_fmac_f32_e32 v134, v103, v103
	v_and_b32_e32 v101, 0xffff0000, v149
	v_fmac_f32_e32 v134, v102, v102
	v_lshlrev_b32_e32 v100, 16, v150
	v_fmac_f32_e32 v134, v101, v101
	v_and_b32_e32 v99, 0xffff0000, v150
	v_fmac_f32_e32 v134, v100, v100
	v_lshlrev_b32_e32 v98, 16, v151
	v_fmac_f32_e32 v134, v99, v99
	v_and_b32_e32 v97, 0xffff0000, v151
	v_fmac_f32_e32 v134, v98, v98
	v_lshlrev_b32_e32 v96, 16, v132
	v_fmac_f32_e32 v134, v97, v97
	v_and_b32_e32 v167, 0xffff0000, v132
	v_fmac_f32_e32 v134, v96, v96
	v_lshlrev_b32_e32 v166, 16, v133
	v_fmac_f32_e32 v134, v167, v167
	v_and_b32_e32 v165, 0xffff0000, v133
	v_fmac_f32_e32 v134, v166, v166
	v_fmac_f32_e32 v134, v165, v165
	v_fmac_f32_e32 v134, v164, v164
	v_and_b32_e32 v152, 0xffff0000, v135
	v_lshlrev_b32_e32 v153, 16, v135
	v_fmac_f32_e32 v134, v163, v163
	v_pk_mul_f32 v[132:133], v[152:153], v[152:153]
	v_and_b32_e32 v150, 0xffff0000, v168
	v_add_f32_e32 v133, v133, v134
	v_lshlrev_b32_e32 v151, 16, v168
	v_add_f32_e32 v134, v132, v133
	v_pk_mul_f32 v[132:133], v[150:151], v[150:151]
	v_and_b32_e32 v148, 0xffff0000, v169
	v_add_f32_e32 v133, v133, v134
	v_lshlrev_b32_e32 v149, 16, v169
	v_add_f32_e32 v134, v132, v133
	v_pk_mul_f32 v[132:133], v[148:149], v[148:149]
	v_lshlrev_b32_e32 v135, 16, v170
	v_add_f32_e32 v133, v133, v134
	v_and_b32_e32 v134, 0xffff0000, v170
	v_add_f32_e32 v162, v132, v133
	v_pk_mul_f32 v[132:133], v[134:135], v[134:135]
	s_nop 0
	v_add_f32_e32 v133, v133, v162
	v_add_f32_e32 v162, v132, v133
	v_and_b32_e32 v132, 0xffff0000, v171
	v_lshlrev_b32_e32 v133, 16, v171
	v_pk_mul_f32 v[168:169], v[132:133], v[132:133]
	s_nop 0
	v_add_f32_e32 v162, v169, v162
	v_add_f32_e32 v162, v168, v162
	s_nop 1
	v_add_f32_dpp v162, v162, v162 quad_perm:[1,0,3,2] row_mask:0xf bank_mask:0xf bound_ctrl:1
	v_fmamk_f32 v162, v162, 0x3c800000, v137
	v_cmp_gt_f32_e64 s[0:1], s4, v162
	v_mul_f32_e32 v168, 0x4b800000, v162
	s_nop 0
	v_cndmask_b32_e64 v162, v162, v168, s[0:1]
	v_rsq_f32_e32 v162, v162
	s_nop 0
	v_mul_f32_e32 v168, 0x45800000, v162
	v_cndmask_b32_e64 v162, v162, v168, s[0:1]
	v_mul_f32_e32 v184, v162, v172
	global_load_dwordx4 v[180:183], v[116:117], off offset:48
	global_load_dwordx4 v[176:179], v[116:117], off offset:32
	global_load_dwordx4 v[172:175], v[116:117], off offset:16
	global_load_dwordx4 v[168:171], v[116:117], off
	v_mul_f32_e32 v111, v162, v111
	v_mul_f32_e32 v110, v162, v110
	v_mul_f32_e32 v109, v162, v109
	v_mul_f32_e32 v108, v162, v108
	v_mul_f32_e32 v107, v162, v107
	v_mul_f32_e32 v106, v162, v106
	v_mul_f32_e32 v105, v162, v105
	v_mul_f32_e32 v104, v162, v104
	v_mul_f32_e32 v103, v162, v103
	v_mul_f32_e32 v102, v162, v102
	v_mul_f32_e32 v101, v162, v101
	v_mul_f32_e32 v100, v162, v100
	v_mul_f32_e32 v99, v162, v99
	v_mul_f32_e32 v98, v162, v98
	v_mul_f32_e32 v97, v162, v97
	s_waitcnt vmcnt(3)
	v_mul_f32_e32 v100, v180, v100
	s_waitcnt vmcnt(2)
	v_mul_f32_e32 v104, v176, v104
	s_waitcnt vmcnt(1)
	v_mul_f32_e32 v108, v172, v108
	s_waitcnt vmcnt(0)
; template <int CTRL> __device__ __forceinline__ float dpp_f(float x) { return __int_as_float(__builtin_amdgcn_update_dpp(0, __float_as_int(x), CTRL, 0xF, 0xF, true)); }
; __device__ __forceinline__ void moba_prep_phase(unsigned char* lds, const bf16_t* H, const float* cosT, const float* sinT, const float* qgain, const float* kgain,
;                                                 bf16_t* Qn, bf16_t* Kimg, bf16_t* VT, float* kmean, int bid, int G, int tid) {
;     ...
;             const float rs = rsqrtf(sq * (1.0f / 64.0f) + 1e-6f);
; #pragma unroll
;             for (int i = 0; i < 32; ++i) { const float xn = x[i] * rs * gn[half * 32 + i]; const float other = dpp_f<DPP_XOR1>(xn); x[i] = half ? (xn * cs[i] + other * sn[i]) : (xn * cs[i] - other * sn[i]); }
	v_mul_f32_e32 v111, v169, v111
	v_mul_f32_e32 v110, v170, v110
	v_mul_f32_e32 v109, v171, v109
	v_mul_f32_dpp v169, v111, v21 quad_perm:[1,0,3,2] row_mask:0xf bank_mask:0xf bound_ctrl:1
	v_cndmask_b32_e64 v169, v169, -v169, vcc
	v_fmac_f32_e32 v169, v1, v111
	v_mul_f32_dpp v111, v110, v22 quad_perm:[1,0,3,2] row_mask:0xf bank_mask:0xf bound_ctrl:1
	v_cndmask_b32_e64 v170, v111, -v111, vcc
	v_fmac_f32_e32 v170, v2, v110
	v_mul_f32_dpp v110, v109, v23 quad_perm:[1,0,3,2] row_mask:0xf bank_mask:0xf bound_ctrl:1
	v_cndmask_b32_e64 v171, v110, -v110, vcc
	v_fmac_f32_e32 v171, v3, v109
	v_mul_f32_dpp v109, v108, v24 quad_perm:[1,0,3,2] row_mask:0xf bank_mask:0xf bound_ctrl:1
	v_cndmask_b32_e64 v172, v109, -v109, vcc
	v_mul_f32_e32 v107, v173, v107
	v_fmac_f32_e32 v172, v4, v108
	v_mul_f32_e32 v106, v174, v106
	v_mul_f32_dpp v108, v107, v25 quad_perm:[1,0,3,2] row_mask:0xf bank_mask:0xf bound_ctrl:1
	v_cndmask_b32_e64 v173, v108, -v108, vcc
	v_fmac_f32_e32 v173, v5, v107
	v_mul_f32_dpp v107, v106, v26 quad_perm:[1,0,3,2] row_mask:0xf bank_mask:0xf bound_ctrl:1
	v_cndmask_b32_e64 v174, v107, -v107, vcc
	v_mul_f32_e32 v105, v175, v105
	v_fmac_f32_e32 v174, v6, v106
	v_mul_f32_e32 v103, v177, v103
	v_mul_f32_dpp v106, v105, v27 quad_perm:[1,0,3,2] row_mask:0xf bank_mask:0xf bound_ctrl:1
	v_cndmask_b32_e64 v175, v106, -v106, vcc
	v_fmac_f32_e32 v175, v7, v105
	v_mul_f32_dpp v105, v104, v28 quad_perm:[1,0,3,2] row_mask:0xf bank_mask:0xf bound_ctrl:1
	v_cndmask_b32_e64 v176, v105, -v105, vcc
	v_fmac_f32_e32 v176, v8, v104
	v_mul_f32_dpp v104, v103, v29 quad_perm:[1,0,3,2] row_mask:0xf bank_mask:0xf bound_ctrl:1
	v_cndmask_b32_e64 v177, v104, -v104, vcc
	v_mul_f32_e32 v102, v178, v102
	v_fmac_f32_e32 v177, v9, v103
	v_mul_f32_e32 v101, v179, v101
	v_mul_f32_dpp v103, v102, v30 quad_perm:[1,0,3,2] row_mask:0xf bank_mask:0xf bound_ctrl:1
	v_cndmask_b32_e64 v178, v103, -v103, vcc
	v_fmac_f32_e32 v178, v10, v102
	v_mul_f32_dpp v102, v101, v31 quad_perm:[1,0,3,2] row_mask:0xf bank_mask:0xf bound_ctrl:1
	v_cndmask_b32_e64 v179, v102, -v102, vcc
	v_fmac_f32_e32 v179, v11, v101
	v_mul_f32_dpp v101, v100, v32 quad_perm:[1,0,3,2] row_mask:0xf bank_mask:0xf bound_ctrl:1
	v_cndmask_b32_e64 v180, v101, -v101, vcc
	v_mul_f32_e32 v99, v181, v99
	v_fmac_f32_e32 v180, v12, v100
	v_mul_f32_e32 v98, v182, v98
	v_mul_f32_dpp v100, v99, v33 quad_perm:[1,0,3,2] row_mask:0xf bank_mask:0xf bound_ctrl:1
	v_cndmask_b32_e64 v181, v100, -v100, vcc
	v_fmac_f32_e32 v181, v13, v99
	v_mul_f32_dpp v99, v98, v34 quad_perm:[1,0,3,2] row_mask:0xf bank_mask:0xf bound_ctrl:1
	v_mul_f32_e32 v184, v168, v184
	v_cndmask_b32_e64 v182, v99, -v99, vcc
	v_mul_f32_e32 v97, v183, v97
	v_mul_f32_dpp v168, v184, v20 quad_perm:[1,0,3,2] row_mask:0xf bank_mask:0xf bound_ctrl:1
	v_fmac_f32_e32 v182, v14, v98
	v_mul_f32_dpp v98, v97, v35 quad_perm:[1,0,3,2] row_mask:0xf bank_mask:0xf bound_ctrl:1
	v_cndmask_b32_e64 v168, v168, -v168, vcc
	v_cndmask_b32_e64 v183, v98, -v98, vcc
	v_fmac_f32_e32 v168, v0, v184
	v_fmac_f32_e32 v183, v15, v97
	v_mul_f32_e32 v184, v162, v96
	global_load_dwordx4 v[96:99], v[116:117], off offset:112
	global_load_dwordx4 v[100:103], v[116:117], off offset:96
	global_load_dwordx4 v[104:107], v[116:117], off offset:80
	global_load_dwordx4 v[108:111], v[116:117], off offset:64
	s_waitcnt vmcnt(0)
	v_mul_f32_e32 v108, v184, v108
	s_nop 1
	v_mul_f32_dpp v184, v108, v36 quad_perm:[1,0,3,2] row_mask:0xf bank_mask:0xf bound_ctrl:1
	v_cndmask_b32_e64 v184, v184, -v184, vcc
	v_fmac_f32_e32 v184, v16, v108
	v_mul_f32_e32 v108, v162, v167
	v_mul_f32_e32 v108, v108, v109
	v_mul_f32_e32 v167, 0x3e38aa3b, v168
	s_nop 0
	v_mul_f32_dpp v109, v108, v37 quad_perm:[1,0,3,2] row_mask:0xf bank_mask:0xf bound_ctrl:1
	v_cndmask_b32_e64 v109, v109, -v109, vcc
	v_fmac_f32_e32 v109, v17, v108
	v_mul_f32_e32 v108, v162, v166
	v_mul_f32_e32 v108, v108, v110
	v_mul_f32_e32 v166, 0x3e38aa3b, v170
	v_mul_f32_e32 v109, 0x3e38aa3b, v109
	v_mul_f32_dpp v110, v108, v38 quad_perm:[1,0,3,2] row_mask:0xf bank_mask:0xf bound_ctrl:1
	v_cndmask_b32_e64 v110, v110, -v110, vcc
	v_fmac_f32_e32 v110, v18, v108
	v_mul_f32_e32 v108, v162, v165
	v_mul_f32_e32 v108, v108, v111
	v_mul_f32_e32 v165, 0x3e38aa3b, v172
	v_mul_f32_e32 v110, 0x3e38aa3b, v110
	v_mul_f32_dpp v111, v108, v39 quad_perm:[1,0,3,2] row_mask:0xf bank_mask:0xf bound_ctrl:1
	v_cndmask_b32_e64 v111, v111, -v111, vcc
	v_fmac_f32_e32 v111, v19, v108
	v_mul_f32_e32 v108, v162, v164
	v_mul_f32_e32 v104, v108, v104
	v_mul_f32_e32 v164, 0x3e38aa3b, v174
	v_mul_f32_e32 v111, 0x3e38aa3b, v111
	v_mul_f32_dpp v108, v104, v40 quad_perm:[1,0,3,2] row_mask:0xf bank_mask:0xf bound_ctrl:1
	v_cndmask_b32_e64 v108, v108, -v108, vcc
	v_fmac_f32_e32 v108, v52, v104
	v_mul_f32_e32 v104, v162, v163
	v_mul_f32_e32 v104, v104, v105
	v_mul_f32_e32 v108, 0x3e38aa3b, v108
	v_mul_f32_e32 v163, 0x3e38aa3b, v176
	v_mul_f32_dpp v105, v104, v41 quad_perm:[1,0,3,2] row_mask:0xf bank_mask:0xf bound_ctrl:1
	v_cndmask_b32_e64 v105, v105, -v105, vcc
	v_fmac_f32_e32 v105, v53, v104
	v_mul_f32_e32 v104, v162, v153
	v_mul_f32_e32 v104, v104, v106
	v_mul_f32_e32 v153, 0x3e38aa3b, v178
	v_mul_f32_e32 v105, 0x3e38aa3b, v105
	v_mul_f32_dpp v106, v104, v42 quad_perm:[1,0,3,2] row_mask:0xf bank_mask:0xf bound_ctrl:1
	v_cndmask_b32_e64 v106, v106, -v106, vcc
	v_fmac_f32_e32 v106, v54, v104
	v_mul_f32_e32 v104, v162, v152
	v_mul_f32_e32 v104, v104, v107
	v_mul_f32_e32 v152, 0x3e38aa3b, v179
	v_mul_f32_e32 v106, 0x3e38aa3b, v106
	v_mul_f32_dpp v107, v104, v43 quad_perm:[1,0,3,2] row_mask:0xf bank_mask:0xf bound_ctrl:1
	v_cndmask_b32_e64 v107, v107, -v107, vcc
	v_fmac_f32_e32 v107, v55, v104
; __device__ __forceinline__ u32x4 pack8(const float* f) { u32x4 w; w.x = cvt_pk_bf16(f[0], f[1]); w.y = cvt_pk_bf16(f[2], f[3]); w.z = cvt_pk_bf16(f[4], f[5]); w.w = cvt_pk_bf16(f[6], f[7]); return w; }
; template <int CTRL> __device__ __forceinline__ float dpp_f(float x) { return __int_as_float(__builtin_amdgcn_update_dpp(0, __float_as_int(x), CTRL, 0xF, 0xF, true)); }
; __device__ __forceinline__ void moba_prep_phase(unsigned char* lds, const bf16_t* H, const float* cosT, const float* sinT, const float* qgain, const float* kgain,
;                                                 bf16_t* Qn, bf16_t* Kimg, bf16_t* VT, float* kmean, int bid, int G, int tid) {
;     ...
;             for (int i = 0; i < 4; ++i) unpack8(raw[which][i], x + 8 * i);
;             float sq = 0.f;
; #pragma unroll
;             for (int i = 0; i < 32; ++i) sq += x[i] * x[i];
;             sq += dpp_f<DPP_XOR1>(sq);
;             const float rs = rsqrtf(sq * (1.0f / 64.0f) + 1e-6f);
;     ...
;             for (int i = 0; i < 32; ++i) { const float xn = x[i] * rs * gn[half * 32 + i]; const float other = dpp_f<DPP_XOR1>(xn); x[i] = half ? (xn * cs[i] + other * sn[i]) : (xn * cs[i] - other * sn[i]); }
;             bf16_t* dst = which ? (Kimg + (size_t)(bh * 64 + n) * 16384 + tk * 64 + half * 32) : (Qn + ((size_t)bh * SEQ + t) * 64 + half * 32);
;             if (!which) {
; #pragma unroll
;                 for (int i = 0; i < 32; ++i) x[i] *= QSCALE;
;             }
; #pragma unroll
;             for (int i = 0; i < 4; ++i) *(u32x4*)(dst + 8 * i) = pack8(x + 8 * i);
	v_mul_f32_e32 v104, v162, v151
	v_mul_f32_e32 v100, v104, v100
	v_mul_f32_e32 v107, 0x3e38aa3b, v107
	v_mul_f32_e32 v151, 0x3e38aa3b, v180
	v_mul_f32_dpp v104, v100, v44 quad_perm:[1,0,3,2] row_mask:0xf bank_mask:0xf bound_ctrl:1
	v_cndmask_b32_e64 v104, v104, -v104, vcc
	v_fmac_f32_e32 v104, v56, v100
	v_mul_f32_e32 v100, v162, v150
	v_mul_f32_e32 v100, v100, v101
	v_mul_f32_e32 v104, 0x3e38aa3b, v104
	s_nop 0
	v_mul_f32_dpp v101, v100, v45 quad_perm:[1,0,3,2] row_mask:0xf bank_mask:0xf bound_ctrl:1
	v_cndmask_b32_e64 v150, v101, -v101, vcc
	v_fmac_f32_e32 v150, v57, v100
	v_mul_f32_e32 v100, v162, v149
	v_mul_f32_e32 v100, v100, v102
	v_mul_f32_e32 v149, 0x3e38aa3b, v182
	s_nop 0
	v_mul_f32_dpp v101, v100, v46 quad_perm:[1,0,3,2] row_mask:0xf bank_mask:0xf bound_ctrl:1
	v_cndmask_b32_e64 v102, v101, -v101, vcc
	v_fmac_f32_e32 v102, v58, v100
	v_mul_f32_e32 v100, v162, v148
	v_mul_f32_e32 v100, v100, v103
	v_mul_f32_e32 v148, 0x3e38aa3b, v183
	v_mul_f32_e32 v102, 0x3e38aa3b, v102
	v_mul_f32_dpp v101, v100, v47 quad_perm:[1,0,3,2] row_mask:0xf bank_mask:0xf bound_ctrl:1
	v_cndmask_b32_e64 v103, v101, -v101, vcc
	v_fmac_f32_e32 v103, v59, v100
	v_mul_f32_e32 v100, v162, v135
	v_mul_f32_e32 v96, v100, v96
	v_mul_f32_e32 v103, 0x3e38aa3b, v103
	s_nop 0
	v_mul_f32_dpp v100, v96, v48 quad_perm:[1,0,3,2] row_mask:0xf bank_mask:0xf bound_ctrl:1
	v_cndmask_b32_e64 v135, v100, -v100, vcc
	v_fmac_f32_e32 v135, v60, v96
	v_mul_f32_e32 v96, v162, v134
	v_mul_f32_e32 v96, v96, v97
	v_lshl_add_u64 v[100:101], v[130:131], 0, v[138:139]
	v_mul_f32_e32 v134, 0x3e38aa3b, v150
	v_mul_f32_dpp v97, v96, v49 quad_perm:[1,0,3,2] row_mask:0xf bank_mask:0xf bound_ctrl:1
	v_cndmask_b32_e64 v97, v97, -v97, vcc
	v_fmac_f32_e32 v97, v61, v96
	v_mul_f32_e32 v96, v162, v133
	v_mul_f32_e32 v96, v96, v98
	v_mul_f32_e32 v150, 0x3e38aa3b, v181
	v_mul_f32_e32 v133, 0x3e38aa3b, v135
	v_mul_f32_dpp v98, v96, v50 quad_perm:[1,0,3,2] row_mask:0xf bank_mask:0xf bound_ctrl:1
	v_cndmask_b32_e64 v98, v98, -v98, vcc
	v_fmac_f32_e32 v98, v62, v96
	v_mul_f32_e32 v96, v162, v132
	v_mul_f32_e32 v96, v96, v99
	v_mul_f32_e32 v131, 0x3e38aa3b, v98
	v_mul_f32_e32 v132, 0x3e38aa3b, v97
	v_mul_f32_dpp v99, v96, v51 quad_perm:[1,0,3,2] row_mask:0xf bank_mask:0xf bound_ctrl:1
	v_cndmask_b32_e64 v99, v99, -v99, vcc
	v_fmac_f32_e32 v99, v63, v96
	v_mul_f32_e32 v130, 0x3e38aa3b, v99
	v_mul_f32_e32 v99, 0x3e38aa3b, v175
	v_mul_f32_e32 v98, 0x3e38aa3b, v173
	v_mul_f32_e32 v97, 0x3e38aa3b, v171
	v_mul_f32_e32 v96, 0x3e38aa3b, v169
	v_cvt_pk_bf16_f32 v96, v167, v96
	v_cvt_pk_bf16_f32 v97, v166, v97
	v_cvt_pk_bf16_f32 v98, v165, v98
	v_cvt_pk_bf16_f32 v99, v164, v99
	v_mul_f32_e32 v162, 0x3e38aa3b, v177
	global_store_dwordx4 v[100:101], v[96:99], off
	v_and_b32_e32 v164, 0xffff0000, v92
	v_mul_f32_e32 v135, 0x3e38aa3b, v184
	v_cvt_pk_bf16_f32 v96, v163, v162
	v_cvt_pk_bf16_f32 v97, v153, v152
	v_cvt_pk_bf16_f32 v98, v151, v150
	v_cvt_pk_bf16_f32 v99, v149, v148
	global_store_dwordx4 v[100:101], v[96:99], off offset:16
	v_lshlrev_b32_e32 v165, 16, v92
	v_lshlrev_b32_e32 v163, 16, v93
	v_cvt_pk_bf16_f32 v96, v135, v109
	v_cvt_pk_bf16_f32 v97, v110, v111
	v_cvt_pk_bf16_f32 v98, v108, v105
	v_cvt_pk_bf16_f32 v99, v106, v107
	v_lshlrev_b32_e32 v108, 16, v86
	v_and_b32_e32 v107, 0xffff0000, v86
	v_mul_f32_e32 v86, v164, v164
	v_fmac_f32_e32 v86, v165, v165
	v_and_b32_e32 v162, 0xffff0000, v93
	v_fmac_f32_e32 v86, v163, v163
	v_lshlrev_b32_e32 v153, 16, v94
	v_fmac_f32_e32 v86, v162, v162
	v_and_b32_e32 v152, 0xffff0000, v94
	v_fmac_f32_e32 v86, v153, v153
	v_lshlrev_b32_e32 v151, 16, v95
	v_fmac_f32_e32 v86, v152, v152
	v_and_b32_e32 v150, 0xffff0000, v95
	v_fmac_f32_e32 v86, v151, v151
	v_lshlrev_b32_e32 v149, 16, v88
	v_fmac_f32_e32 v86, v150, v150
	v_and_b32_e32 v148, 0xffff0000, v88
	v_fmac_f32_e32 v86, v149, v149
	v_lshlrev_b32_e32 v135, 16, v89
	v_fmac_f32_e32 v86, v148, v148
	global_store_dwordx4 v[100:101], v[96:99], off offset:32
	v_fmac_f32_e32 v86, v135, v135
	v_lshlrev_b32_e32 v166, 16, v84
	v_cvt_pk_bf16_f32 v96, v104, v134
	v_and_b32_e32 v134, 0xffff0000, v89
	v_cvt_pk_bf16_f32 v97, v102, v103
	v_cvt_pk_bf16_f32 v98, v133, v132
	v_lshlrev_b32_e32 v133, 16, v90
	v_fmac_f32_e32 v86, v134, v134
	v_and_b32_e32 v132, 0xffff0000, v90
	v_fmac_f32_e32 v86, v133, v133
	v_cvt_pk_bf16_f32 v99, v131, v130
	v_lshlrev_b32_e32 v131, 16, v91
	v_fmac_f32_e32 v86, v132, v132
	v_and_b32_e32 v130, 0xffff0000, v91
	v_fmac_f32_e32 v86, v131, v131
	v_fmac_f32_e32 v86, v130, v130
	v_and_b32_e32 v111, 0xffff0000, v84
	v_fmac_f32_e32 v86, v166, v166
	v_lshlrev_b32_e32 v110, 16, v85
	v_fmac_f32_e32 v86, v111, v111
	v_and_b32_e32 v109, 0xffff0000, v85
	v_fmac_f32_e32 v86, v110, v110
	v_fmac_f32_e32 v86, v109, v109
	v_fmac_f32_e32 v86, v108, v108
	v_and_b32_e32 v104, 0xffff0000, v87
	v_lshlrev_b32_e32 v105, 16, v87
	v_fmac_f32_e32 v86, v107, v107
	v_pk_mul_f32 v[84:85], v[104:105], v[104:105]
	v_and_b32_e32 v102, 0xffff0000, v80
	v_add_f32_e32 v85, v85, v86
	v_lshlrev_b32_e32 v103, 16, v80
	v_add_f32_e32 v86, v84, v85
	v_pk_mul_f32 v[84:85], v[102:103], v[102:103]
	global_store_dwordx4 v[100:101], v[96:99], off offset:48
	v_add_f32_e32 v80, v85, v86
	v_and_b32_e32 v100, 0xffff0000, v81
	v_lshlrev_b32_e32 v101, 16, v81
	v_add_f32_e32 v84, v84, v80
	v_pk_mul_f32 v[80:81], v[100:101], v[100:101]
	v_and_b32_e32 v98, 0xffff0000, v82
	v_add_f32_e32 v81, v81, v84
	v_lshlrev_b32_e32 v99, 16, v82
	v_add_f32_e32 v84, v80, v81
	v_pk_mul_f32 v[80:81], v[98:99], v[98:99]
	v_and_b32_e32 v96, 0xffff0000, v83
	v_add_f32_e32 v81, v81, v84
	v_lshlrev_b32_e32 v97, 16, v83
	v_add_f32_e32 v82, v80, v81
	v_pk_mul_f32 v[80:81], v[96:97], v[96:97]
	s_nop 0
	v_add_f32_e32 v81, v81, v82
	v_add_f32_e32 v80, v80, v81
	s_nop 1
	v_add_f32_dpp v80, v80, v80 quad_perm:[1,0,3,2] row_mask:0xf bank_mask:0xf bound_ctrl:1
	v_fmamk_f32 v80, v80, 0x3c800000, v137
	v_cmp_gt_f32_e64 s[0:1], s4, v80
	v_mul_f32_e32 v81, 0x4b800000, v80
	s_nop 0
	v_cndmask_b32_e64 v80, v80, v81, s[0:1]
	v_rsq_f32_e32 v80, v80
	s_nop 0
	v_mul_f32_e32 v81, 0x45800000, v80
	v_cndmask_b32_e64 v106, v80, v81, s[0:1]
	global_load_dwordx4 v[80:83], v[118:119], off offset:48
	global_load_dwordx4 v[84:87], v[118:119], off offset:32
	global_load_dwordx4 v[88:91], v[118:119], off offset:16
	global_load_dwordx4 v[92:95], v[118:119], off
	v_mul_f32_e32 v165, v106, v165
	v_mul_f32_e32 v166, v106, v166
	s_waitcnt vmcnt(0)
; template <int CTRL> __device__ __forceinline__ float dpp_f(float x) { return __int_as_float(__builtin_amdgcn_update_dpp(0, __float_as_int(x), CTRL, 0xF, 0xF, true)); }
; __device__ __forceinline__ void moba_prep_phase(unsigned char* lds, const bf16_t* H, const float* cosT, const float* sinT, const float* qgain, const float* kgain,
;                                                 bf16_t* Qn, bf16_t* Kimg, bf16_t* VT, float* kmean, int bid, int G, int tid) {
;     ...
;             const float rs = rsqrtf(sq * (1.0f / 64.0f) + 1e-6f);
; #pragma unroll
;             for (int i = 0; i < 32; ++i) { const float xn = x[i] * rs * gn[half * 32 + i]; const float other = dpp_f<DPP_XOR1>(xn); x[i] = half ? (xn * cs[i] + other * sn[i]) : (xn * cs[i] - other * sn[i]); }
	v_mul_f32_e32 v92, v92, v165
	s_nop 1
	v_mul_f32_dpp v165, v92, v20 quad_perm:[1,0,3,2] row_mask:0xf bank_mask:0xf bound_ctrl:1
	v_cndmask_b32_e64 v165, v165, -v165, vcc
	v_fmac_f32_e32 v165, v0, v92
	v_mul_f32_e32 v92, v106, v164
	v_mul_f32_e32 v92, v93, v92
	s_nop 1
	v_mul_f32_dpp v93, v92, v21 quad_perm:[1,0,3,2] row_mask:0xf bank_mask:0xf bound_ctrl:1
	v_cndmask_b32_e64 v164, v93, -v93, vcc
	v_fmac_f32_e32 v164, v1, v92
	v_mul_f32_e32 v92, v106, v163
	v_mul_f32_e32 v92, v94, v92
	s_nop 1
	v_mul_f32_dpp v93, v92, v22 quad_perm:[1,0,3,2] row_mask:0xf bank_mask:0xf bound_ctrl:1
	v_cndmask_b32_e64 v163, v93, -v93, vcc
	v_fmac_f32_e32 v163, v2, v92
	v_mul_f32_e32 v92, v106, v162
	v_mul_f32_e32 v92, v95, v92
	s_nop 1
	v_mul_f32_dpp v93, v92, v23 quad_perm:[1,0,3,2] row_mask:0xf bank_mask:0xf bound_ctrl:1
	v_cndmask_b32_e64 v162, v93, -v93, vcc
	v_fmac_f32_e32 v162, v3, v92
	v_mul_f32_e32 v92, v106, v153
	v_mul_f32_e32 v88, v88, v92
	s_nop 1
	v_mul_f32_dpp v92, v88, v24 quad_perm:[1,0,3,2] row_mask:0xf bank_mask:0xf bound_ctrl:1
	v_cndmask_b32_e64 v153, v92, -v92, vcc
	v_fmac_f32_e32 v153, v4, v88
	v_mul_f32_e32 v88, v106, v152
	v_mul_f32_e32 v88, v88, v89
	s_nop 1
	v_mul_f32_dpp v89, v88, v25 quad_perm:[1,0,3,2] row_mask:0xf bank_mask:0xf bound_ctrl:1
	v_cndmask_b32_e64 v152, v89, -v89, vcc
	v_fmac_f32_e32 v152, v5, v88
	v_mul_f32_e32 v88, v106, v151
	v_mul_f32_e32 v88, v88, v90
	s_nop 1
	v_mul_f32_dpp v89, v88, v26 quad_perm:[1,0,3,2] row_mask:0xf bank_mask:0xf bound_ctrl:1
	v_cndmask_b32_e64 v151, v89, -v89, vcc
	v_fmac_f32_e32 v151, v6, v88
	v_mul_f32_e32 v88, v106, v150
	v_mul_f32_e32 v88, v88, v91
	s_nop 1
	v_mul_f32_dpp v89, v88, v27 quad_perm:[1,0,3,2] row_mask:0xf bank_mask:0xf bound_ctrl:1
	v_cndmask_b32_e64 v150, v89, -v89, vcc
	v_fmac_f32_e32 v150, v7, v88
	v_mul_f32_e32 v88, v106, v149
	v_mul_f32_e32 v84, v88, v84
	s_nop 1
	v_mul_f32_dpp v88, v84, v28 quad_perm:[1,0,3,2] row_mask:0xf bank_mask:0xf bound_ctrl:1
	v_cndmask_b32_e64 v149, v88, -v88, vcc
	v_fmac_f32_e32 v149, v8, v84
	v_mul_f32_e32 v84, v106, v148
	v_mul_f32_e32 v84, v84, v85
	s_nop 1
	v_mul_f32_dpp v85, v84, v29 quad_perm:[1,0,3,2] row_mask:0xf bank_mask:0xf bound_ctrl:1
	v_cndmask_b32_e64 v148, v85, -v85, vcc
	v_fmac_f32_e32 v148, v9, v84
	v_mul_f32_e32 v84, v106, v135
	v_mul_f32_e32 v84, v84, v86
	s_nop 1
	v_mul_f32_dpp v85, v84, v30 quad_perm:[1,0,3,2] row_mask:0xf bank_mask:0xf bound_ctrl:1
	v_cndmask_b32_e64 v135, v85, -v85, vcc
	v_fmac_f32_e32 v135, v10, v84
	v_mul_f32_e32 v84, v106, v134
	v_mul_f32_e32 v84, v84, v87
	s_nop 1
	v_mul_f32_dpp v85, v84, v31 quad_perm:[1,0,3,2] row_mask:0xf bank_mask:0xf bound_ctrl:1
	v_cndmask_b32_e64 v134, v85, -v85, vcc
	v_fmac_f32_e32 v134, v11, v84
	v_mul_f32_e32 v84, v106, v133
	v_mul_f32_e32 v80, v84, v80
	s_nop 1
	v_mul_f32_dpp v84, v80, v32 quad_perm:[1,0,3,2] row_mask:0xf bank_mask:0xf bound_ctrl:1
	v_cndmask_b32_e64 v133, v84, -v84, vcc
	v_fmac_f32_e32 v133, v12, v80
	v_mul_f32_e32 v80, v106, v132
	v_mul_f32_e32 v80, v80, v81
	s_nop 1
	v_mul_f32_dpp v81, v80, v33 quad_perm:[1,0,3,2] row_mask:0xf bank_mask:0xf bound_ctrl:1
	v_cndmask_b32_e64 v132, v81, -v81, vcc
	v_fmac_f32_e32 v132, v13, v80
	v_mul_f32_e32 v80, v106, v131
	v_mul_f32_e32 v80, v80, v82
	s_nop 1
	v_mul_f32_dpp v81, v80, v34 quad_perm:[1,0,3,2] row_mask:0xf bank_mask:0xf bound_ctrl:1
	v_cndmask_b32_e64 v131, v81, -v81, vcc
	v_fmac_f32_e32 v131, v14, v80
	v_mul_f32_e32 v80, v106, v130
	v_mul_f32_e32 v80, v80, v83
	s_nop 1
	v_mul_f32_dpp v81, v80, v35 quad_perm:[1,0,3,2] row_mask:0xf bank_mask:0xf bound_ctrl:1
	v_cndmask_b32_e64 v130, v81, -v81, vcc
	v_fmac_f32_e32 v130, v15, v80
	global_load_dwordx4 v[80:83], v[118:119], off offset:112
	global_load_dwordx4 v[84:87], v[118:119], off offset:96
	global_load_dwordx4 v[88:91], v[118:119], off offset:80
	global_load_dwordx4 v[92:95], v[118:119], off offset:64
	s_waitcnt vmcnt(0)
	v_mul_f32_e32 v92, v166, v92
	s_nop 1
	v_mul_f32_dpp v166, v92, v36 quad_perm:[1,0,3,2] row_mask:0xf bank_mask:0xf bound_ctrl:1
	v_cndmask_b32_e64 v166, v166, -v166, vcc
	v_fmac_f32_e32 v166, v16, v92
	v_mul_f32_e32 v92, v106, v111
	v_mul_f32_e32 v92, v92, v93
	s_nop 1
	v_mul_f32_dpp v93, v92, v37 quad_perm:[1,0,3,2] row_mask:0xf bank_mask:0xf bound_ctrl:1
	v_cndmask_b32_e64 v111, v93, -v93, vcc
	v_fmac_f32_e32 v111, v17, v92
	v_mul_f32_e32 v92, v106, v110
	v_mul_f32_e32 v92, v92, v94
	s_nop 1
	v_mul_f32_dpp v93, v92, v38 quad_perm:[1,0,3,2] row_mask:0xf bank_mask:0xf bound_ctrl:1
	v_cndmask_b32_e64 v110, v93, -v93, vcc
	v_fmac_f32_e32 v110, v18, v92
	v_mul_f32_e32 v92, v106, v109
	v_mul_f32_e32 v92, v92, v95
	s_nop 1
	v_mul_f32_dpp v93, v92, v39 quad_perm:[1,0,3,2] row_mask:0xf bank_mask:0xf bound_ctrl:1
	v_cndmask_b32_e64 v95, v93, -v93, vcc
	v_fmac_f32_e32 v95, v19, v92
	v_mul_f32_e32 v92, v106, v108
	v_mul_f32_e32 v88, v92, v88
	s_nop 1
	v_mul_f32_dpp v92, v88, v40 quad_perm:[1,0,3,2] row_mask:0xf bank_mask:0xf bound_ctrl:1
	v_cndmask_b32_e64 v94, v92, -v92, vcc
	v_fmac_f32_e32 v94, v52, v88
	v_mul_f32_e32 v88, v106, v107
	v_mul_f32_e32 v88, v88, v89
	s_nop 1
	v_mul_f32_dpp v89, v88, v41 quad_perm:[1,0,3,2] row_mask:0xf bank_mask:0xf bound_ctrl:1
	v_cndmask_b32_e64 v93, v89, -v89, vcc
	v_fmac_f32_e32 v93, v53, v88
	v_mul_f32_e32 v88, v106, v105
	v_mul_f32_e32 v88, v88, v90
	s_nop 1
	v_mul_f32_dpp v89, v88, v42 quad_perm:[1,0,3,2] row_mask:0xf bank_mask:0xf bound_ctrl:1
	v_cndmask_b32_e64 v92, v89, -v89, vcc
	v_fmac_f32_e32 v92, v54, v88
	v_mul_f32_e32 v88, v106, v104
	v_mul_f32_e32 v88, v88, v91
	s_nop 1
	v_mul_f32_dpp v89, v88, v43 quad_perm:[1,0,3,2] row_mask:0xf bank_mask:0xf bound_ctrl:1
	v_cndmask_b32_e64 v91, v89, -v89, vcc
; __device__ __forceinline__ u32x4 pack8(const float* f) { u32x4 w; w.x = cvt_pk_bf16(f[0], f[1]); w.y = cvt_pk_bf16(f[2], f[3]); w.z = cvt_pk_bf16(f[4], f[5]); w.w = cvt_pk_bf16(f[6], f[7]); return w; }
; template <int CTRL> __device__ __forceinline__ float dpp_f(float x) { return __int_as_float(__builtin_amdgcn_update_dpp(0, __float_as_int(x), CTRL, 0xF, 0xF, true)); }
; __device__ __forceinline__ void moba_prep_phase(unsigned char* lds, const bf16_t* H, const float* cosT, const float* sinT, const float* qgain, const float* kgain,
;                                                 bf16_t* Qn, bf16_t* Kimg, bf16_t* VT, float* kmean, int bid, int G, int tid) {
;     ...
;             for (int i = 0; i < 32; ++i) { const float xn = x[i] * rs * gn[half * 32 + i]; const float other = dpp_f<DPP_XOR1>(xn); x[i] = half ? (xn * cs[i] + other * sn[i]) : (xn * cs[i] - other * sn[i]); }
;             bf16_t* dst = which ? (Kimg + (size_t)(bh * 64 + n) * 16384 + tk * 64 + half * 32) : (Qn + ((size_t)bh * SEQ + t) * 64 + half * 32);
;             if (!which) {
; #pragma unroll
;                 for (int i = 0; i < 32; ++i) x[i] *= QSCALE;
;             }
; #pragma unroll
;             for (int i = 0; i < 4; ++i) *(u32x4*)(dst + 8 * i) = pack8(x + 8 * i);
;             if (which) {
; #pragma unroll
;                 for (int i = 0; i < 32; ++i) { float s = x[i]; s += dpp_f<DPP_XOR2>(s); s += dpp_f<DPP_ROR4>(s); s += dpp_f<DPP_ROR8>(s); if ((lane & 15) < 2) red[(wave * 4 + (lane >> 4)) * 64 + half * 32 + i] = s; }
	v_fmac_f32_e32 v91, v55, v88
	v_mul_f32_e32 v88, v106, v103
	v_mul_f32_e32 v84, v88, v84
	s_nop 1
	v_mul_f32_dpp v88, v84, v44 quad_perm:[1,0,3,2] row_mask:0xf bank_mask:0xf bound_ctrl:1
	v_cndmask_b32_e64 v90, v88, -v88, vcc
	v_fmac_f32_e32 v90, v56, v84
	v_mul_f32_e32 v84, v106, v102
	v_mul_f32_e32 v84, v84, v85
	s_nop 1
	v_mul_f32_dpp v85, v84, v45 quad_perm:[1,0,3,2] row_mask:0xf bank_mask:0xf bound_ctrl:1
	v_cndmask_b32_e64 v89, v85, -v85, vcc
	v_fmac_f32_e32 v89, v57, v84
	v_mul_f32_e32 v84, v106, v101
	v_mul_f32_e32 v84, v84, v86
	s_nop 1
	v_mul_f32_dpp v85, v84, v46 quad_perm:[1,0,3,2] row_mask:0xf bank_mask:0xf bound_ctrl:1
	v_cndmask_b32_e64 v88, v85, -v85, vcc
	v_fmac_f32_e32 v88, v58, v84
	v_mul_f32_e32 v84, v106, v100
	v_mul_f32_e32 v84, v84, v87
	s_nop 1
	v_mul_f32_dpp v85, v84, v47 quad_perm:[1,0,3,2] row_mask:0xf bank_mask:0xf bound_ctrl:1
	v_cndmask_b32_e64 v86, v85, -v85, vcc
	v_fmac_f32_e32 v86, v59, v84
	v_mul_f32_e32 v84, v106, v99
	v_mul_f32_e32 v80, v84, v80
	s_nop 1
	v_mul_f32_dpp v84, v80, v48 quad_perm:[1,0,3,2] row_mask:0xf bank_mask:0xf bound_ctrl:1
	v_cndmask_b32_e64 v85, v84, -v84, vcc
	v_fmac_f32_e32 v85, v60, v80
	v_mul_f32_e32 v80, v106, v98
	v_mul_f32_e32 v80, v80, v81
	s_nop 1
	v_mul_f32_dpp v81, v80, v49 quad_perm:[1,0,3,2] row_mask:0xf bank_mask:0xf bound_ctrl:1
	v_cndmask_b32_e64 v84, v81, -v81, vcc
	v_fmac_f32_e32 v84, v61, v80
	v_mul_f32_e32 v80, v106, v97
	v_mul_f32_e32 v80, v80, v82
	s_nop 1
	v_mul_f32_dpp v81, v80, v50 quad_perm:[1,0,3,2] row_mask:0xf bank_mask:0xf bound_ctrl:1
	v_cndmask_b32_e64 v81, v81, -v81, vcc
	v_fmac_f32_e32 v81, v62, v80
	v_mul_f32_e32 v80, v106, v96
	v_mul_f32_e32 v82, v80, v83
	v_cvt_pk_bf16_f32 v96, v165, v164
	v_cvt_pk_bf16_f32 v97, v163, v162
	v_cvt_pk_bf16_f32 v98, v153, v152
	v_cvt_pk_bf16_f32 v99, v151, v150
	s_nop 1
	v_mul_f32_dpp v80, v82, v51 quad_perm:[1,0,3,2] row_mask:0xf bank_mask:0xf bound_ctrl:1
	v_cndmask_b32_e64 v80, v80, -v80, vcc
	v_fmac_f32_e32 v80, v63, v82
	v_lshl_add_u64 v[82:83], v[120:121], 0, s[40:41]
	global_store_dwordx4 v[82:83], v[96:99], off
	s_nop 1
	v_cvt_pk_bf16_f32 v96, v149, v148
	v_cvt_pk_bf16_f32 v97, v135, v134
	v_cvt_pk_bf16_f32 v98, v133, v132
	v_cvt_pk_bf16_f32 v99, v131, v130
	global_store_dwordx4 v[82:83], v[96:99], off offset:16
	s_nop 1
	v_cvt_pk_bf16_f32 v96, v166, v111
	v_cvt_pk_bf16_f32 v97, v110, v95
	v_cvt_pk_bf16_f32 v98, v94, v93
	v_cvt_pk_bf16_f32 v99, v92, v91
	global_store_dwordx4 v[82:83], v[96:99], off offset:32
	s_nop 1
	v_cvt_pk_bf16_f32 v96, v90, v89
	v_cvt_pk_bf16_f32 v97, v88, v86
	v_cvt_pk_bf16_f32 v98, v85, v84
	v_cvt_pk_bf16_f32 v99, v81, v80
	global_store_dwordx4 v[82:83], v[96:99], off offset:48
	v_add_f32_dpp v185, v165, v165 quad_perm:[2,3,0,1] row_mask:0xf bank_mask:0xf bound_ctrl:1
	v_add_f32_dpp v186, v164, v164 quad_perm:[2,3,0,1] row_mask:0xf bank_mask:0xf bound_ctrl:1
	v_add_f32_dpp v187, v163, v163 quad_perm:[2,3,0,1] row_mask:0xf bank_mask:0xf bound_ctrl:1
	v_add_f32_dpp v188, v162, v162 quad_perm:[2,3,0,1] row_mask:0xf bank_mask:0xf bound_ctrl:1
	v_add_f32_dpp v189, v153, v153 quad_perm:[2,3,0,1] row_mask:0xf bank_mask:0xf bound_ctrl:1
	v_add_f32_dpp v190, v152, v152 quad_perm:[2,3,0,1] row_mask:0xf bank_mask:0xf bound_ctrl:1
	v_add_f32_dpp v191, v151, v151 quad_perm:[2,3,0,1] row_mask:0xf bank_mask:0xf bound_ctrl:1
	v_add_f32_dpp v192, v150, v150 quad_perm:[2,3,0,1] row_mask:0xf bank_mask:0xf bound_ctrl:1
	v_add_f32_dpp v185, v185, v185 row_ror:4 row_mask:0xf bank_mask:0xf bound_ctrl:1
	v_add_f32_dpp v186, v186, v186 row_ror:4 row_mask:0xf bank_mask:0xf bound_ctrl:1
	v_add_f32_dpp v187, v187, v187 row_ror:4 row_mask:0xf bank_mask:0xf bound_ctrl:1
	v_add_f32_dpp v188, v188, v188 row_ror:4 row_mask:0xf bank_mask:0xf bound_ctrl:1
	v_add_f32_dpp v189, v189, v189 row_ror:4 row_mask:0xf bank_mask:0xf bound_ctrl:1
	v_add_f32_dpp v190, v190, v190 row_ror:4 row_mask:0xf bank_mask:0xf bound_ctrl:1
	v_add_f32_dpp v191, v191, v191 row_ror:4 row_mask:0xf bank_mask:0xf bound_ctrl:1
	v_add_f32_dpp v192, v192, v192 row_ror:4 row_mask:0xf bank_mask:0xf bound_ctrl:1
	v_mov_b32_dpp v193, v185 row_ror:8 row_mask:0xf bank_mask:0xf bound_ctrl:1
	v_mov_b32_dpp v194, v186 row_ror:8 row_mask:0xf bank_mask:0xf bound_ctrl:1
	v_mov_b32_dpp v195, v187 row_ror:8 row_mask:0xf bank_mask:0xf bound_ctrl:1
	v_mov_b32_dpp v196, v188 row_ror:8 row_mask:0xf bank_mask:0xf bound_ctrl:1
	v_mov_b32_dpp v197, v189 row_ror:8 row_mask:0xf bank_mask:0xf bound_ctrl:1
	v_mov_b32_dpp v198, v190 row_ror:8 row_mask:0xf bank_mask:0xf bound_ctrl:1
	v_mov_b32_dpp v199, v191 row_ror:8 row_mask:0xf bank_mask:0xf bound_ctrl:1
	v_mov_b32_dpp v200, v192 row_ror:8 row_mask:0xf bank_mask:0xf bound_ctrl:1
	s_and_saveexec_b64 s[0:1], s[36:37]
	v_add_f32_e32 v185, v185, v193
	v_add_f32_e32 v186, v186, v194
	v_add_f32_e32 v187, v187, v195
	v_add_f32_e32 v188, v188, v196
	v_add_f32_e32 v189, v189, v197
	v_add_f32_e32 v190, v190, v198
	v_add_f32_e32 v191, v191, v199
	v_add_f32_e32 v192, v192, v200
	ds_write_b32 v161, v185
	ds_write_b32 v161, v186 offset:4
	ds_write_b32 v161, v187 offset:8
	ds_write_b32 v161, v188 offset:12
	ds_write_b32 v161, v189 offset:16
	ds_write_b32 v161, v190 offset:20
	ds_write_b32 v161, v191 offset:24
	ds_write_b32 v161, v192 offset:28
	s_or_b64 exec, exec, s[0:1]
	v_add_f32_dpp v185, v149, v149 quad_perm:[2,3,0,1] row_mask:0xf bank_mask:0xf bound_ctrl:1
	v_add_f32_dpp v186, v148, v148 quad_perm:[2,3,0,1] row_mask:0xf bank_mask:0xf bound_ctrl:1
	v_add_f32_dpp v187, v135, v135 quad_perm:[2,3,0,1] row_mask:0xf bank_mask:0xf bound_ctrl:1
	v_add_f32_dpp v188, v134, v134 quad_perm:[2,3,0,1] row_mask:0xf bank_mask:0xf bound_ctrl:1
; template <int CTRL> __device__ __forceinline__ float dpp_f(float x) { return __int_as_float(__builtin_amdgcn_update_dpp(0, __float_as_int(x), CTRL, 0xF, 0xF, true)); }
; __device__ __forceinline__ void moba_prep_phase(unsigned char* lds, const bf16_t* H, const float* cosT, const float* sinT, const float* qgain, const float* kgain,
;                                                 bf16_t* Qn, bf16_t* Kimg, bf16_t* VT, float* kmean, int bid, int G, int tid) {
;     ...
;             if (which) {
; #pragma unroll
;                 for (int i = 0; i < 32; ++i) { float s = x[i]; s += dpp_f<DPP_XOR2>(s); s += dpp_f<DPP_ROR4>(s); s += dpp_f<DPP_ROR8>(s); if ((lane & 15) < 2) red[(wave * 4 + (lane >> 4)) * 64 + half * 32 + i] = s; }
;             }
	v_add_f32_dpp v189, v133, v133 quad_perm:[2,3,0,1] row_mask:0xf bank_mask:0xf bound_ctrl:1
	v_add_f32_dpp v190, v132, v132 quad_perm:[2,3,0,1] row_mask:0xf bank_mask:0xf bound_ctrl:1
	v_add_f32_dpp v191, v131, v131 quad_perm:[2,3,0,1] row_mask:0xf bank_mask:0xf bound_ctrl:1
	v_add_f32_dpp v192, v130, v130 quad_perm:[2,3,0,1] row_mask:0xf bank_mask:0xf bound_ctrl:1
	v_add_f32_dpp v185, v185, v185 row_ror:4 row_mask:0xf bank_mask:0xf bound_ctrl:1
	v_add_f32_dpp v186, v186, v186 row_ror:4 row_mask:0xf bank_mask:0xf bound_ctrl:1
	v_add_f32_dpp v187, v187, v187 row_ror:4 row_mask:0xf bank_mask:0xf bound_ctrl:1
	v_add_f32_dpp v188, v188, v188 row_ror:4 row_mask:0xf bank_mask:0xf bound_ctrl:1
	v_add_f32_dpp v189, v189, v189 row_ror:4 row_mask:0xf bank_mask:0xf bound_ctrl:1
	v_add_f32_dpp v190, v190, v190 row_ror:4 row_mask:0xf bank_mask:0xf bound_ctrl:1
	v_add_f32_dpp v191, v191, v191 row_ror:4 row_mask:0xf bank_mask:0xf bound_ctrl:1
	v_add_f32_dpp v192, v192, v192 row_ror:4 row_mask:0xf bank_mask:0xf bound_ctrl:1
	v_mov_b32_dpp v193, v185 row_ror:8 row_mask:0xf bank_mask:0xf bound_ctrl:1
	v_mov_b32_dpp v194, v186 row_ror:8 row_mask:0xf bank_mask:0xf bound_ctrl:1
	v_mov_b32_dpp v195, v187 row_ror:8 row_mask:0xf bank_mask:0xf bound_ctrl:1
	v_mov_b32_dpp v196, v188 row_ror:8 row_mask:0xf bank_mask:0xf bound_ctrl:1
	v_mov_b32_dpp v197, v189 row_ror:8 row_mask:0xf bank_mask:0xf bound_ctrl:1
	v_mov_b32_dpp v198, v190 row_ror:8 row_mask:0xf bank_mask:0xf bound_ctrl:1
	v_mov_b32_dpp v199, v191 row_ror:8 row_mask:0xf bank_mask:0xf bound_ctrl:1
	v_mov_b32_dpp v200, v192 row_ror:8 row_mask:0xf bank_mask:0xf bound_ctrl:1
	s_and_saveexec_b64 s[0:1], s[36:37]
	v_add_f32_e32 v185, v185, v193
	v_add_f32_e32 v186, v186, v194
	v_add_f32_e32 v187, v187, v195
	v_add_f32_e32 v188, v188, v196
	v_add_f32_e32 v189, v189, v197
	v_add_f32_e32 v190, v190, v198
	v_add_f32_e32 v191, v191, v199
	v_add_f32_e32 v192, v192, v200
	ds_write_b32 v161, v185 offset:32
	ds_write_b32 v161, v186 offset:36
	ds_write_b32 v161, v187 offset:40
	ds_write_b32 v161, v188 offset:44
	ds_write_b32 v161, v189 offset:48
	ds_write_b32 v161, v190 offset:52
	ds_write_b32 v161, v191 offset:56
	ds_write_b32 v161, v192 offset:60
	s_or_b64 exec, exec, s[0:1]
	v_add_f32_dpp v185, v166, v166 quad_perm:[2,3,0,1] row_mask:0xf bank_mask:0xf bound_ctrl:1
	v_add_f32_dpp v186, v111, v111 quad_perm:[2,3,0,1] row_mask:0xf bank_mask:0xf bound_ctrl:1
	v_add_f32_dpp v187, v110, v110 quad_perm:[2,3,0,1] row_mask:0xf bank_mask:0xf bound_ctrl:1
	v_add_f32_dpp v188, v95, v95 quad_perm:[2,3,0,1] row_mask:0xf bank_mask:0xf bound_ctrl:1
	v_add_f32_dpp v189, v94, v94 quad_perm:[2,3,0,1] row_mask:0xf bank_mask:0xf bound_ctrl:1
	v_add_f32_dpp v190, v93, v93 quad_perm:[2,3,0,1] row_mask:0xf bank_mask:0xf bound_ctrl:1
	v_add_f32_dpp v191, v92, v92 quad_perm:[2,3,0,1] row_mask:0xf bank_mask:0xf bound_ctrl:1
	v_add_f32_dpp v192, v91, v91 quad_perm:[2,3,0,1] row_mask:0xf bank_mask:0xf bound_ctrl:1
	v_add_f32_dpp v185, v185, v185 row_ror:4 row_mask:0xf bank_mask:0xf bound_ctrl:1
	v_add_f32_dpp v186, v186, v186 row_ror:4 row_mask:0xf bank_mask:0xf bound_ctrl:1
	v_add_f32_dpp v187, v187, v187 row_ror:4 row_mask:0xf bank_mask:0xf bound_ctrl:1
	v_add_f32_dpp v188, v188, v188 row_ror:4 row_mask:0xf bank_mask:0xf bound_ctrl:1
	v_add_f32_dpp v189, v189, v189 row_ror:4 row_mask:0xf bank_mask:0xf bound_ctrl:1
	v_add_f32_dpp v190, v190, v190 row_ror:4 row_mask:0xf bank_mask:0xf bound_ctrl:1
	v_add_f32_dpp v191, v191, v191 row_ror:4 row_mask:0xf bank_mask:0xf bound_ctrl:1
	v_add_f32_dpp v192, v192, v192 row_ror:4 row_mask:0xf bank_mask:0xf bound_ctrl:1
	v_mov_b32_dpp v193, v185 row_ror:8 row_mask:0xf bank_mask:0xf bound_ctrl:1
	v_mov_b32_dpp v194, v186 row_ror:8 row_mask:0xf bank_mask:0xf bound_ctrl:1
	v_mov_b32_dpp v195, v187 row_ror:8 row_mask:0xf bank_mask:0xf bound_ctrl:1
	v_mov_b32_dpp v196, v188 row_ror:8 row_mask:0xf bank_mask:0xf bound_ctrl:1
	v_mov_b32_dpp v197, v189 row_ror:8 row_mask:0xf bank_mask:0xf bound_ctrl:1
	v_mov_b32_dpp v198, v190 row_ror:8 row_mask:0xf bank_mask:0xf bound_ctrl:1
	v_mov_b32_dpp v199, v191 row_ror:8 row_mask:0xf bank_mask:0xf bound_ctrl:1
	v_mov_b32_dpp v200, v192 row_ror:8 row_mask:0xf bank_mask:0xf bound_ctrl:1
	s_and_saveexec_b64 s[0:1], s[36:37]
	v_add_f32_e32 v185, v185, v193
	v_add_f32_e32 v186, v186, v194
	v_add_f32_e32 v187, v187, v195
	v_add_f32_e32 v188, v188, v196
	v_add_f32_e32 v189, v189, v197
	v_add_f32_e32 v190, v190, v198
	v_add_f32_e32 v191, v191, v199
	v_add_f32_e32 v192, v192, v200
	ds_write_b32 v161, v185 offset:64
	ds_write_b32 v161, v186 offset:68
	ds_write_b32 v161, v187 offset:72
	ds_write_b32 v161, v188 offset:76
	ds_write_b32 v161, v189 offset:80
	ds_write_b32 v161, v190 offset:84
	ds_write_b32 v161, v191 offset:88
	ds_write_b32 v161, v192 offset:92
	s_or_b64 exec, exec, s[0:1]
	v_add_f32_dpp v185, v90, v90 quad_perm:[2,3,0,1] row_mask:0xf bank_mask:0xf bound_ctrl:1
	v_add_f32_dpp v186, v89, v89 quad_perm:[2,3,0,1] row_mask:0xf bank_mask:0xf bound_ctrl:1
	v_add_f32_dpp v187, v88, v88 quad_perm:[2,3,0,1] row_mask:0xf bank_mask:0xf bound_ctrl:1
	v_add_f32_dpp v188, v86, v86 quad_perm:[2,3,0,1] row_mask:0xf bank_mask:0xf bound_ctrl:1
	v_add_f32_dpp v189, v85, v85 quad_perm:[2,3,0,1] row_mask:0xf bank_mask:0xf bound_ctrl:1
	v_add_f32_dpp v190, v84, v84 quad_perm:[2,3,0,1] row_mask:0xf bank_mask:0xf bound_ctrl:1
	v_add_f32_dpp v191, v81, v81 quad_perm:[2,3,0,1] row_mask:0xf bank_mask:0xf bound_ctrl:1
	v_add_f32_dpp v192, v80, v80 quad_perm:[2,3,0,1] row_mask:0xf bank_mask:0xf bound_ctrl:1
; template <int CTRL> __device__ __forceinline__ float dpp_f(float x) { return __int_as_float(__builtin_amdgcn_update_dpp(0, __float_as_int(x), CTRL, 0xF, 0xF, true)); }
; __device__ __forceinline__ int vperm(int k) { return (k & ~31) + (((k & 15) >> 2) << 3) + (((k >> 4) & 1) << 2) + (k & 3); }
; __device__ __forceinline__ void moba_prep_phase(unsigned char* lds, const bf16_t* H, const float* cosT, const float* sinT, const float* qgain, const float* kgain,
;                                                 bf16_t* Qn, bf16_t* Kimg, bf16_t* VT, float* kmean, int bid, int G, int tid) {
;     ...
;                 for (int i = 0; i < 32; ++i) { float s = x[i]; s += dpp_f<DPP_XOR2>(s); s += dpp_f<DPP_ROR4>(s); s += dpp_f<DPP_ROR8>(s); if ((lane & 15) < 2) red[(wave * 4 + (lane >> 4)) * 64 + half * 32 + i] = s; }
;             }
;         }
;         {
; #pragma unroll
;             for (int i = 0; i < 4; ++i) { const u32x4 w = raw[2][i]; const unsigned ww[4] = {w.x, w.y, w.z, w.w};
; #pragma unroll
;                 for (int e = 0; e < 4; ++e) { *(unsigned short*)(vts + (half * 32 + 8 * i + 2 * e) * 528 + vperm(tk) * 2) = (unsigned short)(ww[e] & 0xffffu); *(unsigned short*)(vts + (half * 32 + 8 * i + 2 * e + 1) * 528 + vperm(tk) * 2) = (unsigned short)(ww[e] >> 16); } }
;         }
;         __syncthreads();
;         if (tid < 64) { float s = 0.f;
; #pragma unroll
;             for (int w = 0; w < 32; ++w) s += red[w * 64 + tid];
;             kmean[(size_t)(bh * 64 + n) * 64 + tid] = s * (1.0f / 256.0f); }
	v_add_f32_dpp v185, v185, v185 row_ror:4 row_mask:0xf bank_mask:0xf bound_ctrl:1
	v_add_f32_dpp v186, v186, v186 row_ror:4 row_mask:0xf bank_mask:0xf bound_ctrl:1
	v_add_f32_dpp v187, v187, v187 row_ror:4 row_mask:0xf bank_mask:0xf bound_ctrl:1
	v_add_f32_dpp v188, v188, v188 row_ror:4 row_mask:0xf bank_mask:0xf bound_ctrl:1
	v_add_f32_dpp v189, v189, v189 row_ror:4 row_mask:0xf bank_mask:0xf bound_ctrl:1
	v_add_f32_dpp v190, v190, v190 row_ror:4 row_mask:0xf bank_mask:0xf bound_ctrl:1
	v_add_f32_dpp v191, v191, v191 row_ror:4 row_mask:0xf bank_mask:0xf bound_ctrl:1
	v_add_f32_dpp v192, v192, v192 row_ror:4 row_mask:0xf bank_mask:0xf bound_ctrl:1
	v_mov_b32_dpp v193, v185 row_ror:8 row_mask:0xf bank_mask:0xf bound_ctrl:1
	v_mov_b32_dpp v194, v186 row_ror:8 row_mask:0xf bank_mask:0xf bound_ctrl:1
	v_mov_b32_dpp v195, v187 row_ror:8 row_mask:0xf bank_mask:0xf bound_ctrl:1
	v_mov_b32_dpp v196, v188 row_ror:8 row_mask:0xf bank_mask:0xf bound_ctrl:1
	v_mov_b32_dpp v197, v189 row_ror:8 row_mask:0xf bank_mask:0xf bound_ctrl:1
	v_mov_b32_dpp v198, v190 row_ror:8 row_mask:0xf bank_mask:0xf bound_ctrl:1
	v_mov_b32_dpp v199, v191 row_ror:8 row_mask:0xf bank_mask:0xf bound_ctrl:1
	v_mov_b32_dpp v200, v192 row_ror:8 row_mask:0xf bank_mask:0xf bound_ctrl:1
	s_and_saveexec_b64 s[0:1], s[36:37]
	v_add_f32_e32 v185, v185, v193
	v_add_f32_e32 v186, v186, v194
	v_add_f32_e32 v187, v187, v195
	v_add_f32_e32 v188, v188, v196
	v_add_f32_e32 v189, v189, v197
	v_add_f32_e32 v190, v190, v198
	v_add_f32_e32 v191, v191, v199
	v_add_f32_e32 v192, v192, v200
	ds_write_b32 v161, v185 offset:96
	ds_write_b32 v161, v186 offset:100
	ds_write_b32 v161, v187 offset:104
	ds_write_b32 v161, v188 offset:108
	ds_write_b32 v161, v189 offset:112
	ds_write_b32 v161, v190 offset:116
	ds_write_b32 v161, v191 offset:120
	ds_write_b32 v161, v192 offset:124
	s_or_b64 exec, exec, s[0:1]
	ds_write_b16 v156, v76 offset:8192
	ds_write_b16_d16_hi v156, v76 offset:8720
	ds_write_b16 v156, v77 offset:9248
	ds_write_b16_d16_hi v156, v77 offset:9776
	ds_write_b16 v156, v78 offset:10304
	ds_write_b16_d16_hi v156, v78 offset:10832
	ds_write_b16 v156, v79 offset:11360
	ds_write_b16_d16_hi v156, v79 offset:11888
	ds_write_b16 v156, v72 offset:12416
	ds_write_b16_d16_hi v156, v72 offset:12944
	ds_write_b16 v156, v73 offset:13472
	ds_write_b16_d16_hi v156, v73 offset:14000
	ds_write_b16 v156, v74 offset:14528
	ds_write_b16_d16_hi v156, v74 offset:15056
	ds_write_b16 v156, v75 offset:15584
	ds_write_b16_d16_hi v156, v75 offset:16112
	ds_write_b16 v156, v68 offset:16640
	ds_write_b16_d16_hi v156, v68 offset:17168
	ds_write_b16 v156, v69 offset:17696
	ds_write_b16_d16_hi v156, v69 offset:18224
	ds_write_b16 v156, v70 offset:18752
	ds_write_b16_d16_hi v156, v70 offset:19280
	ds_write_b16 v156, v71 offset:19808
	ds_write_b16_d16_hi v156, v71 offset:20336
	ds_write_b16 v156, v64 offset:20864
	ds_write_b16_d16_hi v156, v64 offset:21392
	ds_write_b16 v156, v65 offset:21920
	ds_write_b16_d16_hi v156, v65 offset:22448
	ds_write_b16 v156, v66 offset:22976
	ds_write_b16_d16_hi v156, v66 offset:23504
	ds_write_b16 v156, v67 offset:24032
	ds_write_b16_d16_hi v156, v67 offset:24560
	s_waitcnt lgkmcnt(0)
	s_barrier
	s_and_saveexec_b64 s[0:1], s[38:39]
	s_cbranch_execz .LBB0_502
	ds_read2st64_b32 v[64:65], v155 offset1:1
	s_lshl_b64 s[26:27], s[46:47], 8
	s_waitcnt lgkmcnt(0)
	v_add_f32_e32 v64, 0, v64
	v_add_f32_e32 v66, v64, v65
	ds_read2st64_b32 v[64:65], v155 offset0:2 offset1:3
	s_waitcnt lgkmcnt(0)
	v_add_f32_e32 v64, v66, v64
	v_add_f32_e32 v66, v64, v65
	ds_read2st64_b32 v[64:65], v155 offset0:4 offset1:5
	s_waitcnt lgkmcnt(0)
	v_add_f32_e32 v64, v66, v64
	v_add_f32_e32 v66, v64, v65
	ds_read2st64_b32 v[64:65], v155 offset0:6 offset1:7
	s_waitcnt lgkmcnt(0)
	v_add_f32_e32 v64, v66, v64
	v_add_f32_e32 v66, v64, v65
	ds_read2st64_b32 v[64:65], v155 offset0:8 offset1:9
	s_waitcnt lgkmcnt(0)
	v_add_f32_e32 v64, v66, v64
	v_add_f32_e32 v66, v64, v65
	ds_read2st64_b32 v[64:65], v155 offset0:10 offset1:11
	s_waitcnt lgkmcnt(0)
	v_add_f32_e32 v64, v66, v64
	v_add_f32_e32 v66, v64, v65
	ds_read2st64_b32 v[64:65], v155 offset0:12 offset1:13
	s_waitcnt lgkmcnt(0)
	v_add_f32_e32 v64, v66, v64
	v_add_f32_e32 v66, v64, v65
	ds_read2st64_b32 v[64:65], v155 offset0:14 offset1:15
	s_waitcnt lgkmcnt(0)
	v_add_f32_e32 v64, v66, v64
	v_add_f32_e32 v66, v64, v65
	ds_read2st64_b32 v[64:65], v155 offset0:16 offset1:17
	s_waitcnt lgkmcnt(0)
	v_add_f32_e32 v64, v66, v64
	v_add_f32_e32 v66, v64, v65
	ds_read2st64_b32 v[64:65], v155 offset0:18 offset1:19
	s_waitcnt lgkmcnt(0)
	v_add_f32_e32 v64, v66, v64
	v_add_f32_e32 v66, v64, v65
	ds_read2st64_b32 v[64:65], v155 offset0:20 offset1:21
	s_waitcnt lgkmcnt(0)
	v_add_f32_e32 v64, v66, v64
	v_add_f32_e32 v66, v64, v65
	ds_read2st64_b32 v[64:65], v155 offset0:22 offset1:23
	s_waitcnt lgkmcnt(0)
	v_add_f32_e32 v64, v66, v64
	v_add_f32_e32 v66, v64, v65
	ds_read2st64_b32 v[64:65], v155 offset0:24 offset1:25
	s_waitcnt lgkmcnt(0)
	v_add_f32_e32 v64, v66, v64
	v_add_f32_e32 v66, v64, v65
	ds_read2st64_b32 v[64:65], v155 offset0:26 offset1:27
	s_waitcnt lgkmcnt(0)
	v_add_f32_e32 v64, v66, v64
	v_add_f32_e32 v66, v64, v65
	ds_read2st64_b32 v[64:65], v155 offset0:28 offset1:29
	s_waitcnt lgkmcnt(0)
	v_add_f32_e32 v64, v66, v64
	v_add_f32_e32 v66, v64, v65
	ds_read2st64_b32 v[64:65], v155 offset0:30 offset1:31
	s_waitcnt lgkmcnt(0)
	v_add_f32_e32 v64, v66, v64
	v_add_f32_e32 v64, v64, v65
	v_mul_f32_e32 v66, 0x3b800000, v64
	v_lshl_add_u64 v[64:65], v[112:113], 0, s[26:27]
	global_store_dword v[64:65], v66, off
	s_branch .LBB0_502
